# attention QK accumulator chains made contiguous (p0 x4 then p1 x4) on top of previous version
# speedup vs baseline: 1.0013x; 1.0013x over previous
; __device__ __forceinline__ void attn_unit(Frame& F, int b, int h, int qb, const bf16* QKVU, bf16* ATT, float lam, const float* subln_g, const unsigned* kmaxw) {
;     ...
;             { const float base = slope2 * (float)(kv0 - q0) - m_run;
; #pragma unroll
;               for (int r = 0; r < 16; ++r) { p0[r] = ab[r] + base; p1[r] = p0[r] + 32.f * slope2; } }
;             __builtin_amdgcn_s_setprio(1);
; #pragma unroll
;             for (int d0 = 0; d0 < 4; ++d0) { const bf16x8 k0 = *(const LAS bf16x8*)(Kb + koff[d0]), k1 = *(const LAS bf16x8*)(Kb + 8192 + koff[d0]);
;                 p0 = __builtin_amdgcn_mfma_f32_32x32x16_bf16(k0, qr[d0], p0, 0, 0, 0); p1 = __builtin_amdgcn_mfma_f32_32x32x16_bf16(k1, qr[d0], p1, 0, 0, 0); }
;             __builtin_amdgcn_s_setprio(0);
;             if (kv0 + 63 > qw0) { const int qpos = qw0 + r32;
; #pragma unroll
;                 for (int r = 0; r < 16; ++r) { const int kv = kv0 + crow(r, hi); if (kv > qpos) p0[r] = -INFINITY; if (kv + 32 > qpos) p1[r] = -INFINITY; } }
;             float mx = fmaxf(fmaxf(p0[0], p0[1]), p1[0]), mx2 = fmaxf(fmaxf(p0[2], p0[3]), p1[1]);
;             mx = fmaxf(fmaxf(mx, p1[2]), p1[3]);
; #pragma unroll
;             for (int r = 4; r < 16; r += 4) { mx = fmaxf(fmaxf(mx, p0[r]), p0[r + 1]); mx2 = fmaxf(fmaxf(mx2, p0[r + 2]), p0[r + 3]); mx = fmaxf(fmaxf(mx, p1[r]), p1[r + 1]); mx2 = fmaxf(fmaxf(mx2, p1[r + 2]), p1[r + 3]); }
;             mx = fmaxf(mx, mx2);
;             mx = fmaxf(mx, __shfl_xor(mx, 32));
;             bool sub = false; float delta = 0.f;
;             if (!started) { delta = mx; started = true; sub = true; }
;             else if (__any(mx > THR_RESC)) { delta = fmaxf(mx, 0.f); sub = true; const float f = __builtin_amdgcn_exp2f(-delta); l_sum *= f;
; #pragma unroll
;                 for (int c = 0; c < 4; ++c)
; #pragma unroll
;                     for (int r = 0; r < 16; ++r) o[c][r] *= f; }
;             if (sub) { m_run += delta;
; #pragma unroll
;                 for (int r = 0; r < 16; ++r) { p0[r] -= delta; p1[r] -= delta; } }
;             float ls = 0.f, ls2 = 0.f;
; #pragma unroll
;             for (int r = 0; r < 16; ++r) { p0[r] = __builtin_amdgcn_exp2f(p0[r]); p1[r] = __builtin_amdgcn_exp2f(p1[r]); ls += p0[r]; ls2 += p1[r]; }
;             l_sum += ls + ls2;
;             bf16x8 pf[2][2];
; #pragma unroll
;             for (int s = 0; s < 2; ++s) { v4u a, c;
.LBB0_520:
	s_xor_b64 s[12:13], s[12:13], -1
	s_andn2_b64 vcc, exec, s[12:13]
	s_mov_b64 s[12:13], -1
	s_cbranch_vccnz .LBB0_530
	s_add_i32 s22, s33, s67
	s_cmp_gt_u32 s22, s9
	s_mov_b64 s[12:13], 0
	s_cbranch_scc1 .LBB0_530
	v_cvt_f32_i32_e32 v66, s67
	s_lshl_b32 s12, s66, 15
	v_mov_b32_e32 v175, v174
	s_add_i32 s12, s12, 0
	v_fma_f32 v80, v114, v66, -v176
	v_add_f32_e32 v66, v158, v80
	v_add_f32_e32 v67, v159, v80
	v_add_f32_e32 v68, v160, v80
	v_add_f32_e32 v69, v161, v80
	v_add_f32_e32 v70, v162, v80
	v_add_f32_e32 v71, v163, v80
	v_add_f32_e32 v72, v164, v80
	v_add_f32_e32 v73, v165, v80
	v_add_f32_e32 v74, v166, v80
	v_add_f32_e32 v75, v167, v80
	v_add_f32_e32 v76, v168, v80
	v_add_f32_e32 v77, v169, v80
	v_add_f32_e32 v78, v170, v80
	v_add_f32_e32 v79, v171, v80
	v_add_f32_e32 v81, v173, v80
	v_add_f32_e32 v80, v172, v80
	v_add_f32_e32 v94, v174, v78
	v_add_f32_e32 v95, v175, v79
	v_add_f32_e32 v96, v174, v80
	v_add_f32_e32 v97, v175, v81
	v_add_f32_e32 v92, v174, v76
	v_add_f32_e32 v93, v175, v77
	v_add_f32_e32 v90, v174, v74
	v_add_f32_e32 v91, v175, v75
	v_add_f32_e32 v88, v174, v72
	v_add_f32_e32 v89, v175, v73
	v_add_f32_e32 v86, v174, v70
	v_add_f32_e32 v87, v175, v71
	v_add_f32_e32 v84, v174, v68
	v_add_f32_e32 v85, v175, v69
	v_add_f32_e32 v82, v178, v66
	v_add_f32_e32 v83, v179, v67
	s_setprio 1
	s_waitcnt lgkmcnt(0)
	v_mfma_f32_32x32x16_bf16 v[66:81], v[200:203], v[98:101], v[66:81]
	v_mfma_f32_32x32x16_bf16 v[66:81], v[218:221], v[102:105], v[66:81]
	v_mfma_f32_32x32x16_bf16 v[66:81], v[226:229], v[106:109], v[66:81]
	v_mfma_f32_32x32x16_bf16 v[66:81], v[238:241], v[110:113], v[66:81]
	v_mfma_f32_32x32x16_bf16 v[82:97], v[204:207], v[98:101], v[82:97]
	v_mfma_f32_32x32x16_bf16 v[82:97], v[222:225], v[102:105], v[82:97]
	v_mfma_f32_32x32x16_bf16 v[82:97], v[230:233], v[106:109], v[82:97]
	v_mfma_f32_32x32x16_bf16 v[82:97], v[242:245], v[110:113], v[82:97]
	s_setprio 0
	v_add_u32_e32 v204, s12, v184
	v_add_u32_e32 v208, s12, v188
	v_add_u32_e32 v205, s12, v185
	v_add_u32_e32 v209, s12, v189
	v_add_u32_e32 v206, s12, v186
	v_add_u32_e32 v210, s12, v190
	v_add_u32_e32 v207, s12, v187
	v_add_u32_e32 v211, s12, v191
	ds_read_b64_tr_b16 v[218:219], v204 offset:16384
	ds_read_b64_tr_b16 v[220:221], v208 offset:16384
	ds_read_b64_tr_b16 v[222:223], v205 offset:16384
	ds_read_b64_tr_b16 v[224:225], v209 offset:16384
	ds_read_b64_tr_b16 v[226:227], v206 offset:16384
	ds_read_b64_tr_b16 v[228:229], v210 offset:16384
	ds_read_b64_tr_b16 v[230:231], v207 offset:16384
	ds_read_b64_tr_b16 v[232:233], v211 offset:16384
	ds_read_b64_tr_b16 v[238:239], v204 offset:20480
	ds_read_b64_tr_b16 v[240:241], v208 offset:20480
	ds_read_b64_tr_b16 v[242:243], v205 offset:20480
	ds_read_b64_tr_b16 v[244:245], v209 offset:20480
	ds_read_b64_tr_b16 v[246:247], v206 offset:20480
	ds_read_b64_tr_b16 v[248:249], v210 offset:20480
	ds_read_b64_tr_b16 v[212:213], v207 offset:20480
	ds_read_b64_tr_b16 v[214:215], v211 offset:20480
	s_add_i32 s22, s22, 63
	s_cmp_le_u32 s22, s62
	s_cbranch_scc1 .LBB0_524
	v_add_u32_e32 v120, s67, v198
	v_cmp_lt_u32_e32 vcc, v120, v155
	v_add_u32_e32 v175, 2, v120
	s_nop 2
	v_cndmask_b32_e32 v67, v197, v67, vcc
	v_cmp_le_u32_e32 vcc, v120, v155
	s_nop 1
	v_cndmask_b32_e32 v66, v197, v66, vcc
	v_cmp_lt_i32_e32 vcc, v120, v157
	s_nop 1
	v_cndmask_b32_e32 v83, v197, v83, vcc
	v_cmp_le_i32_e32 vcc, v120, v157
	s_nop 1
	v_cndmask_b32_e32 v82, v197, v82, vcc
	v_cmp_le_u32_e32 vcc, v175, v155
	s_nop 1
	v_cndmask_b32_e32 v68, v197, v68, vcc
	v_cmp_le_i32_e32 vcc, v175, v157
	v_add_u32_e32 v175, 3, v120
	s_nop 0
	v_cndmask_b32_e32 v84, v197, v84, vcc
	v_cmp_le_u32_e32 vcc, v175, v155
	s_nop 1
	v_cndmask_b32_e32 v69, v197, v69, vcc
	v_cmp_le_i32_e32 vcc, v175, v157
	v_add_u32_e32 v175, 8, v120
	s_nop 0
	v_cndmask_b32_e32 v85, v197, v85, vcc
	v_cmp_le_u32_e32 vcc, v175, v155
	s_nop 1
	v_cndmask_b32_e32 v70, v197, v70, vcc
	v_cmp_le_i32_e32 vcc, v175, v157
	v_add_u32_e32 v175, 9, v120
	s_nop 0
	v_cndmask_b32_e32 v86, v197, v86, vcc
	v_cmp_le_u32_e32 vcc, v175, v155
	s_nop 1
	v_cndmask_b32_e32 v71, v197, v71, vcc
	v_cmp_le_i32_e32 vcc, v175, v157
	v_add_u32_e32 v175, 10, v120
	s_nop 0
	v_cndmask_b32_e32 v87, v197, v87, vcc
	v_cmp_le_u32_e32 vcc, v175, v155
	s_nop 1
	v_cndmask_b32_e32 v72, v197, v72, vcc
	v_cmp_le_i32_e32 vcc, v175, v157
	v_add_u32_e32 v175, 11, v120
	s_nop 0
	v_cndmask_b32_e32 v88, v197, v88, vcc
	v_cmp_le_u32_e32 vcc, v175, v155
	s_nop 1
	v_cndmask_b32_e32 v73, v197, v73, vcc
	v_cmp_le_i32_e32 vcc, v175, v157
	v_add_u32_e32 v175, 16, v120
	s_nop 0
	v_cndmask_b32_e32 v89, v197, v89, vcc
	v_cmp_le_u32_e32 vcc, v175, v155
	s_nop 1
	v_cndmask_b32_e32 v74, v197, v74, vcc
	v_cmp_le_i32_e32 vcc, v175, v157
	v_add_u32_e32 v175, 17, v120
	s_nop 0
	v_cndmask_b32_e32 v90, v197, v90, vcc
	v_cmp_le_u32_e32 vcc, v175, v155
	s_nop 1
	v_cndmask_b32_e32 v75, v197, v75, vcc
	v_cmp_le_i32_e32 vcc, v175, v157
	v_add_u32_e32 v175, 18, v120
	s_nop 0
	v_cndmask_b32_e32 v91, v197, v91, vcc
	v_cmp_le_u32_e32 vcc, v175, v155
	s_nop 1
	v_cndmask_b32_e32 v76, v197, v76, vcc
	v_cmp_le_i32_e32 vcc, v175, v157
	v_add_u32_e32 v175, 19, v120
	s_nop 0
	v_cndmask_b32_e32 v92, v197, v92, vcc
	v_cmp_le_u32_e32 vcc, v175, v155
	s_nop 1
	v_cndmask_b32_e32 v77, v197, v77, vcc
	v_cmp_le_i32_e32 vcc, v175, v157
	v_add_u32_e32 v175, 24, v120
	s_nop 0
	v_cndmask_b32_e32 v93, v197, v93, vcc
	v_cmp_le_u32_e32 vcc, v175, v155
	s_nop 1
	v_cndmask_b32_e32 v78, v197, v78, vcc
	v_cmp_le_i32_e32 vcc, v175, v157
	v_add_u32_e32 v175, 25, v120
	s_nop 0
	v_cndmask_b32_e32 v94, v197, v94, vcc
	v_cmp_le_u32_e32 vcc, v175, v155
	s_nop 1
	v_cndmask_b32_e32 v79, v197, v79, vcc
	v_cmp_le_i32_e32 vcc, v175, v157
	v_add_u32_e32 v175, 26, v120
	v_add_u32_e32 v120, 27, v120
	v_cndmask_b32_e32 v95, v197, v95, vcc
	v_cmp_le_u32_e32 vcc, v175, v155
	s_nop 1
	v_cndmask_b32_e32 v80, v197, v80, vcc
	v_cmp_le_i32_e32 vcc, v175, v157
	s_nop 1
	v_cndmask_b32_e32 v96, v197, v96, vcc
	v_cmp_le_u32_e32 vcc, v120, v155
	s_nop 1
	v_cndmask_b32_e32 v81, v197, v81, vcc
	v_cmp_le_i32_e32 vcc, v120, v157
	s_nop 1
	v_cndmask_b32_e32 v97, v197, v97, vcc
